# hand-written norm-row item in P0 (all 8 rows of a wave in flight, params loaded once, DPP row sums)
# speedup vs baseline: 1.0179x; 1.0179x over previous
.LBB0_56:
	s_load_dwordx2 s[52:53], s[0:1], 0x0
	s_load_dwordx2 s[58:59], s[0:1], 0x10
	s_load_dwordx2 s[56:57], s[0:1], 0x30
	s_sub_i32 s36, s45, s70
	s_lshl_b32 s8, s36, 6
	s_lshl_b32 s9, s29, 3
	s_add_i32 s8, s8, s9
	s_mov_b32 s9, 0
	v_lshlrev_b32_e32 v66, 4, v80
	v_lshlrev_b32_e32 v82, 3, v80
	s_lshl_b64 s[64:65], s[8:9], 11
	s_add_u32 s64, s72, s64
	s_addc_u32 s65, s73, s65
	s_lshr_b32 s54, s8, 13
	s_mul_i32 s54, s54, 0x6000
	s_add_u32 s60, s18, s54
	s_addc_u32 s61, s19, 0
	s_lshl_b64 s[62:63], s[8:9], 12
	s_waitcnt lgkmcnt(0)
	s_add_u32 s62, s52, s62
	s_addc_u32 s63, s53, s63
	s_cmpk_lt_i32 s8, 0x4000
	s_cbranch_scc1 .Lnorm_lat
	s_add_i32 s54, s8, 0xffffc000
	s_mov_b32 s55, 0
	s_lshl_b64 s[62:63], s[54:55], 12
	s_add_u32 s62, s58, s62
	s_addc_u32 s63, s59, s63
	s_mov_b64 s[60:61], s[16:17]
.Lnorm_lat:
	s_add_u32 s68, s60, 0x1000
	s_addc_u32 s69, s61, 0
	global_load_dwordx4 v[2:5], v66, s[56:57]
	global_load_dwordx4 v[6:9], v66, s[56:57] offset:1024
	global_load_dwordx4 v[10:13], v66, s[56:57] offset:2048
	global_load_dwordx4 v[14:17], v66, s[56:57] offset:3072
	global_load_dwordx4 v[18:21], v66, s[68:69]
	global_load_dwordx4 v[22:25], v66, s[68:69] offset:1024
	global_load_dwordx4 v[26:29], v66, s[68:69] offset:2048
	global_load_dwordx4 v[30:33], v66, s[68:69] offset:3072
	global_load_dwordx4 v[34:37], v66, s[60:61]
	global_load_dwordx4 v[38:41], v66, s[60:61] offset:1024
	global_load_dwordx4 v[42:45], v66, s[60:61] offset:2048
	global_load_dwordx4 v[46:49], v66, s[60:61] offset:3072
	global_load_dwordx4 v[106:109], v66, s[62:63] nt
	global_load_dwordx4 v[110:113], v66, s[62:63] offset:1024 nt
	global_load_dwordx4 v[114:117], v66, s[62:63] offset:2048 nt
	global_load_dwordx4 v[118:121], v66, s[62:63] offset:3072 nt
	s_add_u32 s62, s62, 0x1000
	s_addc_u32 s63, s63, 0
	global_load_dwordx4 v[122:125], v66, s[62:63] nt
	global_load_dwordx4 v[126:129], v66, s[62:63] offset:1024 nt
	global_load_dwordx4 v[130:133], v66, s[62:63] offset:2048 nt
	global_load_dwordx4 v[134:137], v66, s[62:63] offset:3072 nt
	s_add_u32 s62, s62, 0x1000
	s_addc_u32 s63, s63, 0
	global_load_dwordx4 v[138:141], v66, s[62:63] nt
	global_load_dwordx4 v[142:145], v66, s[62:63] offset:1024 nt
	global_load_dwordx4 v[146:149], v66, s[62:63] offset:2048 nt
	global_load_dwordx4 v[150:153], v66, s[62:63] offset:3072 nt
	s_add_u32 s62, s62, 0x1000
	s_addc_u32 s63, s63, 0
	global_load_dwordx4 v[154:157], v66, s[62:63] nt
	global_load_dwordx4 v[158:161], v66, s[62:63] offset:1024 nt
	global_load_dwordx4 v[162:165], v66, s[62:63] offset:2048 nt
	global_load_dwordx4 v[166:169], v66, s[62:63] offset:3072 nt
	s_add_u32 s62, s62, 0x1000
	s_addc_u32 s63, s63, 0
	global_load_dwordx4 v[170:173], v66, s[62:63] nt
	global_load_dwordx4 v[174:177], v66, s[62:63] offset:1024 nt
	global_load_dwordx4 v[178:181], v66, s[62:63] offset:2048 nt
	global_load_dwordx4 v[182:185], v66, s[62:63] offset:3072 nt
	s_add_u32 s62, s62, 0x1000
	s_addc_u32 s63, s63, 0
	global_load_dwordx4 v[186:189], v66, s[62:63] nt
	global_load_dwordx4 v[190:193], v66, s[62:63] offset:1024 nt
	global_load_dwordx4 v[194:197], v66, s[62:63] offset:2048 nt
	global_load_dwordx4 v[198:201], v66, s[62:63] offset:3072 nt
	s_add_u32 s62, s62, 0x1000
	s_addc_u32 s63, s63, 0
	global_load_dwordx4 v[202:205], v66, s[62:63] nt
	global_load_dwordx4 v[206:209], v66, s[62:63] offset:1024 nt
	global_load_dwordx4 v[210:213], v66, s[62:63] offset:2048 nt
	global_load_dwordx4 v[214:217], v66, s[62:63] offset:3072 nt
	s_add_u32 s62, s62, 0x1000
	s_addc_u32 s63, s63, 0
	global_load_dwordx4 v[218:221], v66, s[62:63] nt
	global_load_dwordx4 v[222:225], v66, s[62:63] offset:1024 nt
	global_load_dwordx4 v[226:229], v66, s[62:63] offset:2048 nt
	global_load_dwordx4 v[230:233], v66, s[62:63] offset:3072 nt
	s_waitcnt vmcnt(36)
	v_pk_add_f32 v[18:19], v[18:19], 1.0 op_sel_hi:[1,0]
	v_pk_add_f32 v[20:21], v[20:21], 1.0 op_sel_hi:[1,0]
	v_pk_add_f32 v[22:23], v[22:23], 1.0 op_sel_hi:[1,0]
	v_pk_add_f32 v[24:25], v[24:25], 1.0 op_sel_hi:[1,0]
	v_pk_add_f32 v[26:27], v[26:27], 1.0 op_sel_hi:[1,0]
	v_pk_add_f32 v[28:29], v[28:29], 1.0 op_sel_hi:[1,0]
	v_pk_add_f32 v[30:31], v[30:31], 1.0 op_sel_hi:[1,0]
	v_pk_add_f32 v[32:33], v[32:33], 1.0 op_sel_hi:[1,0]
	v_pk_mul_f32 v[2:3], v[2:3], v[18:19]
	v_pk_mul_f32 v[4:5], v[4:5], v[20:21]
	v_pk_mul_f32 v[6:7], v[6:7], v[22:23]
	v_pk_mul_f32 v[8:9], v[8:9], v[24:25]
	v_pk_mul_f32 v[10:11], v[10:11], v[26:27]
	v_pk_mul_f32 v[12:13], v[12:13], v[28:29]
	v_pk_mul_f32 v[14:15], v[14:15], v[30:31]
	v_pk_mul_f32 v[16:17], v[16:17], v[32:33]
	s_waitcnt vmcnt(16)
	v_pk_mul_f32 v[86:87], v[106:107], v[106:107]
	v_pk_mul_f32 v[88:89], v[108:109], v[108:109]
	v_pk_mul_f32 v[90:91], v[122:123], v[122:123]
	v_pk_mul_f32 v[92:93], v[124:125], v[124:125]
	v_pk_mul_f32 v[94:95], v[138:139], v[138:139]
	v_pk_mul_f32 v[96:97], v[140:141], v[140:141]
	v_pk_mul_f32 v[98:99], v[154:155], v[154:155]
	v_pk_mul_f32 v[100:101], v[156:157], v[156:157]
	v_pk_fma_f32 v[86:87], v[110:111], v[110:111], v[86:87]
	v_pk_fma_f32 v[88:89], v[112:113], v[112:113], v[88:89]
	v_pk_fma_f32 v[90:91], v[126:127], v[126:127], v[90:91]
	v_pk_fma_f32 v[92:93], v[128:129], v[128:129], v[92:93]
	v_pk_fma_f32 v[94:95], v[142:143], v[142:143], v[94:95]
	v_pk_fma_f32 v[96:97], v[144:145], v[144:145], v[96:97]
	v_pk_fma_f32 v[98:99], v[158:159], v[158:159], v[98:99]
	v_pk_fma_f32 v[100:101], v[160:161], v[160:161], v[100:101]
	v_pk_fma_f32 v[86:87], v[114:115], v[114:115], v[86:87]
	v_pk_fma_f32 v[88:89], v[116:117], v[116:117], v[88:89]
	v_pk_fma_f32 v[90:91], v[130:131], v[130:131], v[90:91]
	v_pk_fma_f32 v[92:93], v[132:133], v[132:133], v[92:93]
	v_pk_fma_f32 v[94:95], v[146:147], v[146:147], v[94:95]
	v_pk_fma_f32 v[96:97], v[148:149], v[148:149], v[96:97]
	v_pk_fma_f32 v[98:99], v[162:163], v[162:163], v[98:99]
	v_pk_fma_f32 v[100:101], v[164:165], v[164:165], v[100:101]
	v_pk_fma_f32 v[86:87], v[118:119], v[118:119], v[86:87]
	v_pk_fma_f32 v[88:89], v[120:121], v[120:121], v[88:89]
	v_pk_fma_f32 v[90:91], v[134:135], v[134:135], v[90:91]
	v_pk_fma_f32 v[92:93], v[136:137], v[136:137], v[92:93]
	v_pk_fma_f32 v[94:95], v[150:151], v[150:151], v[94:95]
	v_pk_fma_f32 v[96:97], v[152:153], v[152:153], v[96:97]
	v_pk_fma_f32 v[98:99], v[166:167], v[166:167], v[98:99]
	v_pk_fma_f32 v[100:101], v[168:169], v[168:169], v[100:101]
	v_pk_add_f32 v[86:87], v[86:87], v[88:89]
	v_pk_add_f32 v[90:91], v[90:91], v[92:93]
	v_pk_add_f32 v[94:95], v[94:95], v[96:97]
	v_pk_add_f32 v[98:99], v[98:99], v[100:101]
	v_add_f32_e32 v50, v86, v87
	v_add_f32_e32 v51, v90, v91
	v_add_f32_e32 v52, v94, v95
	v_add_f32_e32 v53, v98, v99
	v_add_f32_dpp v50, v50, v50 quad_perm:[1,0,3,2] row_mask:0xf bank_mask:0xf
	v_add_f32_dpp v51, v51, v51 quad_perm:[1,0,3,2] row_mask:0xf bank_mask:0xf
	v_add_f32_dpp v52, v52, v52 quad_perm:[1,0,3,2] row_mask:0xf bank_mask:0xf
	v_add_f32_dpp v53, v53, v53 quad_perm:[1,0,3,2] row_mask:0xf bank_mask:0xf
	v_add_f32_dpp v50, v50, v50 quad_perm:[2,3,0,1] row_mask:0xf bank_mask:0xf
	v_add_f32_dpp v51, v51, v51 quad_perm:[2,3,0,1] row_mask:0xf bank_mask:0xf
	v_add_f32_dpp v52, v52, v52 quad_perm:[2,3,0,1] row_mask:0xf bank_mask:0xf
	v_add_f32_dpp v53, v53, v53 quad_perm:[2,3,0,1] row_mask:0xf bank_mask:0xf
	v_add_f32_dpp v50, v50, v50 row_half_mirror row_mask:0xf bank_mask:0xf
	v_add_f32_dpp v51, v51, v51 row_half_mirror row_mask:0xf bank_mask:0xf
	v_add_f32_dpp v52, v52, v52 row_half_mirror row_mask:0xf bank_mask:0xf
	v_add_f32_dpp v53, v53, v53 row_half_mirror row_mask:0xf bank_mask:0xf
	v_add_f32_dpp v50, v50, v50 row_mirror row_mask:0xf bank_mask:0xf
	v_add_f32_dpp v51, v51, v51 row_mirror row_mask:0xf bank_mask:0xf
	v_add_f32_dpp v52, v52, v52 row_mirror row_mask:0xf bank_mask:0xf
	v_add_f32_dpp v53, v53, v53 row_mirror row_mask:0xf bank_mask:0xf
	v_add_f32_dpp v50, v50, v50 row_bcast:15 row_mask:0xa bank_mask:0xf
	v_add_f32_dpp v51, v51, v51 row_bcast:15 row_mask:0xa bank_mask:0xf
	v_add_f32_dpp v52, v52, v52 row_bcast:15 row_mask:0xa bank_mask:0xf
	v_add_f32_dpp v53, v53, v53 row_bcast:15 row_mask:0xa bank_mask:0xf
	v_add_f32_dpp v50, v50, v50 row_bcast:31 row_mask:0xc bank_mask:0xf
	v_add_f32_dpp v51, v51, v51 row_bcast:31 row_mask:0xc bank_mask:0xf
	v_add_f32_dpp v52, v52, v52 row_bcast:31 row_mask:0xc bank_mask:0xf
	v_add_f32_dpp v53, v53, v53 row_bcast:31 row_mask:0xc bank_mask:0xf
	v_readlane_b32 s52, v50, 63
	v_readlane_b32 s53, v51, 63
	v_readlane_b32 s54, v52, 63
	v_readlane_b32 s55, v53, 63
	v_mov_b32_e32 v60, s52
	v_mov_b32_e32 v62, s53
	v_mov_b32_e32 v64, s54
	v_mov_b32_e32 v84, s55
	v_fmamk_f32 v60, v60, 0x3a800000, v68
	v_fmamk_f32 v62, v62, 0x3a800000, v68
	v_fmamk_f32 v64, v64, 0x3a800000, v68
	v_fmamk_f32 v84, v84, 0x3a800000, v68
	v_rsq_f32_e32 v60, v60
	v_rsq_f32_e32 v62, v62
	v_rsq_f32_e32 v64, v64
	v_rsq_f32_e32 v84, v84
	v_pk_mul_f32 v[106:107], v[60:61], v[106:107] op_sel_hi:[0,1]
	v_pk_mul_f32 v[108:109], v[60:61], v[108:109] op_sel_hi:[0,1]
	v_pk_mul_f32 v[110:111], v[60:61], v[110:111] op_sel_hi:[0,1]
	v_pk_mul_f32 v[112:113], v[60:61], v[112:113] op_sel_hi:[0,1]
	v_pk_mul_f32 v[114:115], v[60:61], v[114:115] op_sel_hi:[0,1]
	v_pk_mul_f32 v[116:117], v[60:61], v[116:117] op_sel_hi:[0,1]
	v_pk_mul_f32 v[118:119], v[60:61], v[118:119] op_sel_hi:[0,1]
	v_pk_mul_f32 v[120:121], v[60:61], v[120:121] op_sel_hi:[0,1]
	v_pk_fma_f32 v[106:107], v[106:107], v[2:3], v[34:35]
	v_pk_fma_f32 v[108:109], v[108:109], v[4:5], v[36:37]
	v_pk_fma_f32 v[110:111], v[110:111], v[6:7], v[38:39]
	v_pk_fma_f32 v[112:113], v[112:113], v[8:9], v[40:41]
	v_pk_fma_f32 v[114:115], v[114:115], v[10:11], v[42:43]
	v_pk_fma_f32 v[116:117], v[116:117], v[12:13], v[44:45]
	v_pk_fma_f32 v[118:119], v[118:119], v[14:15], v[46:47]
	v_pk_fma_f32 v[120:121], v[120:121], v[16:17], v[48:49]
	v_cvt_pk_bf16_f32 v106, v106, v107
	v_cvt_pk_bf16_f32 v107, v108, v109
	v_cvt_pk_bf16_f32 v110, v110, v111
	v_cvt_pk_bf16_f32 v111, v112, v113
	v_cvt_pk_bf16_f32 v114, v114, v115
	v_cvt_pk_bf16_f32 v115, v116, v117
	v_cvt_pk_bf16_f32 v118, v118, v119
	v_cvt_pk_bf16_f32 v119, v120, v121
	global_store_dwordx2 v82, v[106:107], s[64:65]
	global_store_dwordx2 v82, v[110:111], s[64:65] offset:512
	global_store_dwordx2 v82, v[114:115], s[64:65] offset:1024
	global_store_dwordx2 v82, v[118:119], s[64:65] offset:1536
	s_add_u32 s64, s64, 0x800
	s_addc_u32 s65, s65, 0
	v_pk_mul_f32 v[122:123], v[62:63], v[122:123] op_sel_hi:[0,1]
	v_pk_mul_f32 v[124:125], v[62:63], v[124:125] op_sel_hi:[0,1]
	v_pk_mul_f32 v[126:127], v[62:63], v[126:127] op_sel_hi:[0,1]
	v_pk_mul_f32 v[128:129], v[62:63], v[128:129] op_sel_hi:[0,1]
	v_pk_mul_f32 v[130:131], v[62:63], v[130:131] op_sel_hi:[0,1]
	v_pk_mul_f32 v[132:133], v[62:63], v[132:133] op_sel_hi:[0,1]
	v_pk_mul_f32 v[134:135], v[62:63], v[134:135] op_sel_hi:[0,1]
	v_pk_mul_f32 v[136:137], v[62:63], v[136:137] op_sel_hi:[0,1]
	v_pk_fma_f32 v[122:123], v[122:123], v[2:3], v[34:35]
	v_pk_fma_f32 v[124:125], v[124:125], v[4:5], v[36:37]
	v_pk_fma_f32 v[126:127], v[126:127], v[6:7], v[38:39]
	v_pk_fma_f32 v[128:129], v[128:129], v[8:9], v[40:41]
	v_pk_fma_f32 v[130:131], v[130:131], v[10:11], v[42:43]
	v_pk_fma_f32 v[132:133], v[132:133], v[12:13], v[44:45]
	v_pk_fma_f32 v[134:135], v[134:135], v[14:15], v[46:47]
	v_pk_fma_f32 v[136:137], v[136:137], v[16:17], v[48:49]
	v_cvt_pk_bf16_f32 v122, v122, v123
	v_cvt_pk_bf16_f32 v123, v124, v125
	v_cvt_pk_bf16_f32 v126, v126, v127
	v_cvt_pk_bf16_f32 v127, v128, v129
	v_cvt_pk_bf16_f32 v130, v130, v131
	v_cvt_pk_bf16_f32 v131, v132, v133
	v_cvt_pk_bf16_f32 v134, v134, v135
	v_cvt_pk_bf16_f32 v135, v136, v137
	global_store_dwordx2 v82, v[122:123], s[64:65]
	global_store_dwordx2 v82, v[126:127], s[64:65] offset:512
	global_store_dwordx2 v82, v[130:131], s[64:65] offset:1024
	global_store_dwordx2 v82, v[134:135], s[64:65] offset:1536
	s_add_u32 s64, s64, 0x800
	s_addc_u32 s65, s65, 0
	v_pk_mul_f32 v[138:139], v[64:65], v[138:139] op_sel_hi:[0,1]
	v_pk_mul_f32 v[140:141], v[64:65], v[140:141] op_sel_hi:[0,1]
	v_pk_mul_f32 v[142:143], v[64:65], v[142:143] op_sel_hi:[0,1]
	v_pk_mul_f32 v[144:145], v[64:65], v[144:145] op_sel_hi:[0,1]
	v_pk_mul_f32 v[146:147], v[64:65], v[146:147] op_sel_hi:[0,1]
	v_pk_mul_f32 v[148:149], v[64:65], v[148:149] op_sel_hi:[0,1]
	v_pk_mul_f32 v[150:151], v[64:65], v[150:151] op_sel_hi:[0,1]
	v_pk_mul_f32 v[152:153], v[64:65], v[152:153] op_sel_hi:[0,1]
	v_pk_fma_f32 v[138:139], v[138:139], v[2:3], v[34:35]
	v_pk_fma_f32 v[140:141], v[140:141], v[4:5], v[36:37]
	v_pk_fma_f32 v[142:143], v[142:143], v[6:7], v[38:39]
	v_pk_fma_f32 v[144:145], v[144:145], v[8:9], v[40:41]
	v_pk_fma_f32 v[146:147], v[146:147], v[10:11], v[42:43]
	v_pk_fma_f32 v[148:149], v[148:149], v[12:13], v[44:45]
	v_pk_fma_f32 v[150:151], v[150:151], v[14:15], v[46:47]
	v_pk_fma_f32 v[152:153], v[152:153], v[16:17], v[48:49]
	v_cvt_pk_bf16_f32 v138, v138, v139
	v_cvt_pk_bf16_f32 v139, v140, v141
	v_cvt_pk_bf16_f32 v142, v142, v143
	v_cvt_pk_bf16_f32 v143, v144, v145
	v_cvt_pk_bf16_f32 v146, v146, v147
	v_cvt_pk_bf16_f32 v147, v148, v149
	v_cvt_pk_bf16_f32 v150, v150, v151
	v_cvt_pk_bf16_f32 v151, v152, v153
	global_store_dwordx2 v82, v[138:139], s[64:65]
	global_store_dwordx2 v82, v[142:143], s[64:65] offset:512
	global_store_dwordx2 v82, v[146:147], s[64:65] offset:1024
	global_store_dwordx2 v82, v[150:151], s[64:65] offset:1536
	s_add_u32 s64, s64, 0x800
	s_addc_u32 s65, s65, 0
	v_pk_mul_f32 v[154:155], v[84:85], v[154:155] op_sel_hi:[0,1]
	v_pk_mul_f32 v[156:157], v[84:85], v[156:157] op_sel_hi:[0,1]
	v_pk_mul_f32 v[158:159], v[84:85], v[158:159] op_sel_hi:[0,1]
	v_pk_mul_f32 v[160:161], v[84:85], v[160:161] op_sel_hi:[0,1]
	v_pk_mul_f32 v[162:163], v[84:85], v[162:163] op_sel_hi:[0,1]
	v_pk_mul_f32 v[164:165], v[84:85], v[164:165] op_sel_hi:[0,1]
	v_pk_mul_f32 v[166:167], v[84:85], v[166:167] op_sel_hi:[0,1]
	v_pk_mul_f32 v[168:169], v[84:85], v[168:169] op_sel_hi:[0,1]
	v_pk_fma_f32 v[154:155], v[154:155], v[2:3], v[34:35]
	v_pk_fma_f32 v[156:157], v[156:157], v[4:5], v[36:37]
	v_pk_fma_f32 v[158:159], v[158:159], v[6:7], v[38:39]
	v_pk_fma_f32 v[160:161], v[160:161], v[8:9], v[40:41]
	v_pk_fma_f32 v[162:163], v[162:163], v[10:11], v[42:43]
	v_pk_fma_f32 v[164:165], v[164:165], v[12:13], v[44:45]
	v_pk_fma_f32 v[166:167], v[166:167], v[14:15], v[46:47]
	v_pk_fma_f32 v[168:169], v[168:169], v[16:17], v[48:49]
	v_cvt_pk_bf16_f32 v154, v154, v155
	v_cvt_pk_bf16_f32 v155, v156, v157
	v_cvt_pk_bf16_f32 v158, v158, v159
	v_cvt_pk_bf16_f32 v159, v160, v161
	v_cvt_pk_bf16_f32 v162, v162, v163
	v_cvt_pk_bf16_f32 v163, v164, v165
	v_cvt_pk_bf16_f32 v166, v166, v167
	v_cvt_pk_bf16_f32 v167, v168, v169
	global_store_dwordx2 v82, v[154:155], s[64:65]
	global_store_dwordx2 v82, v[158:159], s[64:65] offset:512
	global_store_dwordx2 v82, v[162:163], s[64:65] offset:1024
	global_store_dwordx2 v82, v[166:167], s[64:65] offset:1536
	s_add_u32 s64, s64, 0x800
	s_addc_u32 s65, s65, 0
	s_waitcnt vmcnt(16)
	v_pk_mul_f32 v[86:87], v[170:171], v[170:171]
	v_pk_mul_f32 v[88:89], v[172:173], v[172:173]
	v_pk_mul_f32 v[90:91], v[186:187], v[186:187]
	v_pk_mul_f32 v[92:93], v[188:189], v[188:189]
	v_pk_mul_f32 v[94:95], v[202:203], v[202:203]
	v_pk_mul_f32 v[96:97], v[204:205], v[204:205]
	v_pk_mul_f32 v[98:99], v[218:219], v[218:219]
	v_pk_mul_f32 v[100:101], v[220:221], v[220:221]
	v_pk_fma_f32 v[86:87], v[174:175], v[174:175], v[86:87]
	v_pk_fma_f32 v[88:89], v[176:177], v[176:177], v[88:89]
	v_pk_fma_f32 v[90:91], v[190:191], v[190:191], v[90:91]
	v_pk_fma_f32 v[92:93], v[192:193], v[192:193], v[92:93]
	v_pk_fma_f32 v[94:95], v[206:207], v[206:207], v[94:95]
	v_pk_fma_f32 v[96:97], v[208:209], v[208:209], v[96:97]
	v_pk_fma_f32 v[98:99], v[222:223], v[222:223], v[98:99]
	v_pk_fma_f32 v[100:101], v[224:225], v[224:225], v[100:101]
	v_pk_fma_f32 v[86:87], v[178:179], v[178:179], v[86:87]
	v_pk_fma_f32 v[88:89], v[180:181], v[180:181], v[88:89]
	v_pk_fma_f32 v[90:91], v[194:195], v[194:195], v[90:91]
	v_pk_fma_f32 v[92:93], v[196:197], v[196:197], v[92:93]
	v_pk_fma_f32 v[94:95], v[210:211], v[210:211], v[94:95]
	v_pk_fma_f32 v[96:97], v[212:213], v[212:213], v[96:97]
	v_pk_fma_f32 v[98:99], v[226:227], v[226:227], v[98:99]
	v_pk_fma_f32 v[100:101], v[228:229], v[228:229], v[100:101]
	v_pk_fma_f32 v[86:87], v[182:183], v[182:183], v[86:87]
	v_pk_fma_f32 v[88:89], v[184:185], v[184:185], v[88:89]
	v_pk_fma_f32 v[90:91], v[198:199], v[198:199], v[90:91]
	v_pk_fma_f32 v[92:93], v[200:201], v[200:201], v[92:93]
	v_pk_fma_f32 v[94:95], v[214:215], v[214:215], v[94:95]
	v_pk_fma_f32 v[96:97], v[216:217], v[216:217], v[96:97]
	v_pk_fma_f32 v[98:99], v[230:231], v[230:231], v[98:99]
	v_pk_fma_f32 v[100:101], v[232:233], v[232:233], v[100:101]
	v_pk_add_f32 v[86:87], v[86:87], v[88:89]
	v_pk_add_f32 v[90:91], v[90:91], v[92:93]
	v_pk_add_f32 v[94:95], v[94:95], v[96:97]
	v_pk_add_f32 v[98:99], v[98:99], v[100:101]
	v_add_f32_e32 v50, v86, v87
	v_add_f32_e32 v51, v90, v91
	v_add_f32_e32 v52, v94, v95
	v_add_f32_e32 v53, v98, v99
	v_add_f32_dpp v50, v50, v50 quad_perm:[1,0,3,2] row_mask:0xf bank_mask:0xf
	v_add_f32_dpp v51, v51, v51 quad_perm:[1,0,3,2] row_mask:0xf bank_mask:0xf
	v_add_f32_dpp v52, v52, v52 quad_perm:[1,0,3,2] row_mask:0xf bank_mask:0xf
	v_add_f32_dpp v53, v53, v53 quad_perm:[1,0,3,2] row_mask:0xf bank_mask:0xf
	v_add_f32_dpp v50, v50, v50 quad_perm:[2,3,0,1] row_mask:0xf bank_mask:0xf
	v_add_f32_dpp v51, v51, v51 quad_perm:[2,3,0,1] row_mask:0xf bank_mask:0xf
	v_add_f32_dpp v52, v52, v52 quad_perm:[2,3,0,1] row_mask:0xf bank_mask:0xf
	v_add_f32_dpp v53, v53, v53 quad_perm:[2,3,0,1] row_mask:0xf bank_mask:0xf
	v_add_f32_dpp v50, v50, v50 row_half_mirror row_mask:0xf bank_mask:0xf
	v_add_f32_dpp v51, v51, v51 row_half_mirror row_mask:0xf bank_mask:0xf
	v_add_f32_dpp v52, v52, v52 row_half_mirror row_mask:0xf bank_mask:0xf
	v_add_f32_dpp v53, v53, v53 row_half_mirror row_mask:0xf bank_mask:0xf
	v_add_f32_dpp v50, v50, v50 row_mirror row_mask:0xf bank_mask:0xf
	v_add_f32_dpp v51, v51, v51 row_mirror row_mask:0xf bank_mask:0xf
	v_add_f32_dpp v52, v52, v52 row_mirror row_mask:0xf bank_mask:0xf
	v_add_f32_dpp v53, v53, v53 row_mirror row_mask:0xf bank_mask:0xf
	v_add_f32_dpp v50, v50, v50 row_bcast:15 row_mask:0xa bank_mask:0xf
	v_add_f32_dpp v51, v51, v51 row_bcast:15 row_mask:0xa bank_mask:0xf
	v_add_f32_dpp v52, v52, v52 row_bcast:15 row_mask:0xa bank_mask:0xf
	v_add_f32_dpp v53, v53, v53 row_bcast:15 row_mask:0xa bank_mask:0xf
	v_add_f32_dpp v50, v50, v50 row_bcast:31 row_mask:0xc bank_mask:0xf
	v_add_f32_dpp v51, v51, v51 row_bcast:31 row_mask:0xc bank_mask:0xf
	v_add_f32_dpp v52, v52, v52 row_bcast:31 row_mask:0xc bank_mask:0xf
	v_add_f32_dpp v53, v53, v53 row_bcast:31 row_mask:0xc bank_mask:0xf
	v_readlane_b32 s52, v50, 63
	v_readlane_b32 s53, v51, 63
	v_readlane_b32 s54, v52, 63
	v_readlane_b32 s55, v53, 63
	v_mov_b32_e32 v60, s52
	v_mov_b32_e32 v62, s53
	v_mov_b32_e32 v64, s54
	v_mov_b32_e32 v84, s55
	v_fmamk_f32 v60, v60, 0x3a800000, v68
	v_fmamk_f32 v62, v62, 0x3a800000, v68
	v_fmamk_f32 v64, v64, 0x3a800000, v68
	v_fmamk_f32 v84, v84, 0x3a800000, v68
	v_rsq_f32_e32 v60, v60
	v_rsq_f32_e32 v62, v62
	v_rsq_f32_e32 v64, v64
	v_rsq_f32_e32 v84, v84
	v_pk_mul_f32 v[170:171], v[60:61], v[170:171] op_sel_hi:[0,1]
	v_pk_mul_f32 v[172:173], v[60:61], v[172:173] op_sel_hi:[0,1]
	v_pk_mul_f32 v[174:175], v[60:61], v[174:175] op_sel_hi:[0,1]
	v_pk_mul_f32 v[176:177], v[60:61], v[176:177] op_sel_hi:[0,1]
	v_pk_mul_f32 v[178:179], v[60:61], v[178:179] op_sel_hi:[0,1]
	v_pk_mul_f32 v[180:181], v[60:61], v[180:181] op_sel_hi:[0,1]
	v_pk_mul_f32 v[182:183], v[60:61], v[182:183] op_sel_hi:[0,1]
	v_pk_mul_f32 v[184:185], v[60:61], v[184:185] op_sel_hi:[0,1]
	v_pk_fma_f32 v[170:171], v[170:171], v[2:3], v[34:35]
	v_pk_fma_f32 v[172:173], v[172:173], v[4:5], v[36:37]
	v_pk_fma_f32 v[174:175], v[174:175], v[6:7], v[38:39]
	v_pk_fma_f32 v[176:177], v[176:177], v[8:9], v[40:41]
	v_pk_fma_f32 v[178:179], v[178:179], v[10:11], v[42:43]
	v_pk_fma_f32 v[180:181], v[180:181], v[12:13], v[44:45]
	v_pk_fma_f32 v[182:183], v[182:183], v[14:15], v[46:47]
	v_pk_fma_f32 v[184:185], v[184:185], v[16:17], v[48:49]
	v_cvt_pk_bf16_f32 v170, v170, v171
	v_cvt_pk_bf16_f32 v171, v172, v173
	v_cvt_pk_bf16_f32 v174, v174, v175
	v_cvt_pk_bf16_f32 v175, v176, v177
	v_cvt_pk_bf16_f32 v178, v178, v179
	v_cvt_pk_bf16_f32 v179, v180, v181
	v_cvt_pk_bf16_f32 v182, v182, v183
	v_cvt_pk_bf16_f32 v183, v184, v185
	global_store_dwordx2 v82, v[170:171], s[64:65]
	global_store_dwordx2 v82, v[174:175], s[64:65] offset:512
	global_store_dwordx2 v82, v[178:179], s[64:65] offset:1024
	global_store_dwordx2 v82, v[182:183], s[64:65] offset:1536
	s_add_u32 s64, s64, 0x800
	s_addc_u32 s65, s65, 0
	v_pk_mul_f32 v[186:187], v[62:63], v[186:187] op_sel_hi:[0,1]
	v_pk_mul_f32 v[188:189], v[62:63], v[188:189] op_sel_hi:[0,1]
	v_pk_mul_f32 v[190:191], v[62:63], v[190:191] op_sel_hi:[0,1]
	v_pk_mul_f32 v[192:193], v[62:63], v[192:193] op_sel_hi:[0,1]
	v_pk_mul_f32 v[194:195], v[62:63], v[194:195] op_sel_hi:[0,1]
	v_pk_mul_f32 v[196:197], v[62:63], v[196:197] op_sel_hi:[0,1]
	v_pk_mul_f32 v[198:199], v[62:63], v[198:199] op_sel_hi:[0,1]
	v_pk_mul_f32 v[200:201], v[62:63], v[200:201] op_sel_hi:[0,1]
	v_pk_fma_f32 v[186:187], v[186:187], v[2:3], v[34:35]
	v_pk_fma_f32 v[188:189], v[188:189], v[4:5], v[36:37]
	v_pk_fma_f32 v[190:191], v[190:191], v[6:7], v[38:39]
	v_pk_fma_f32 v[192:193], v[192:193], v[8:9], v[40:41]
	v_pk_fma_f32 v[194:195], v[194:195], v[10:11], v[42:43]
	v_pk_fma_f32 v[196:197], v[196:197], v[12:13], v[44:45]
	v_pk_fma_f32 v[198:199], v[198:199], v[14:15], v[46:47]
	v_pk_fma_f32 v[200:201], v[200:201], v[16:17], v[48:49]
	v_cvt_pk_bf16_f32 v186, v186, v187
	v_cvt_pk_bf16_f32 v187, v188, v189
	v_cvt_pk_bf16_f32 v190, v190, v191
	v_cvt_pk_bf16_f32 v191, v192, v193
	v_cvt_pk_bf16_f32 v194, v194, v195
	v_cvt_pk_bf16_f32 v195, v196, v197
	v_cvt_pk_bf16_f32 v198, v198, v199
	v_cvt_pk_bf16_f32 v199, v200, v201
	global_store_dwordx2 v82, v[186:187], s[64:65]
	global_store_dwordx2 v82, v[190:191], s[64:65] offset:512
	global_store_dwordx2 v82, v[194:195], s[64:65] offset:1024
	global_store_dwordx2 v82, v[198:199], s[64:65] offset:1536
	s_add_u32 s64, s64, 0x800
	s_addc_u32 s65, s65, 0
	v_pk_mul_f32 v[202:203], v[64:65], v[202:203] op_sel_hi:[0,1]
	v_pk_mul_f32 v[204:205], v[64:65], v[204:205] op_sel_hi:[0,1]
	v_pk_mul_f32 v[206:207], v[64:65], v[206:207] op_sel_hi:[0,1]
	v_pk_mul_f32 v[208:209], v[64:65], v[208:209] op_sel_hi:[0,1]
	v_pk_mul_f32 v[210:211], v[64:65], v[210:211] op_sel_hi:[0,1]
	v_pk_mul_f32 v[212:213], v[64:65], v[212:213] op_sel_hi:[0,1]
	v_pk_mul_f32 v[214:215], v[64:65], v[214:215] op_sel_hi:[0,1]
	v_pk_mul_f32 v[216:217], v[64:65], v[216:217] op_sel_hi:[0,1]
	v_pk_fma_f32 v[202:203], v[202:203], v[2:3], v[34:35]
	v_pk_fma_f32 v[204:205], v[204:205], v[4:5], v[36:37]
	v_pk_fma_f32 v[206:207], v[206:207], v[6:7], v[38:39]
	v_pk_fma_f32 v[208:209], v[208:209], v[8:9], v[40:41]
	v_pk_fma_f32 v[210:211], v[210:211], v[10:11], v[42:43]
	v_pk_fma_f32 v[212:213], v[212:213], v[12:13], v[44:45]
	v_pk_fma_f32 v[214:215], v[214:215], v[14:15], v[46:47]
	v_pk_fma_f32 v[216:217], v[216:217], v[16:17], v[48:49]
	v_cvt_pk_bf16_f32 v202, v202, v203
	v_cvt_pk_bf16_f32 v203, v204, v205
	v_cvt_pk_bf16_f32 v206, v206, v207
	v_cvt_pk_bf16_f32 v207, v208, v209
	v_cvt_pk_bf16_f32 v210, v210, v211
	v_cvt_pk_bf16_f32 v211, v212, v213
	v_cvt_pk_bf16_f32 v214, v214, v215
	v_cvt_pk_bf16_f32 v215, v216, v217
	global_store_dwordx2 v82, v[202:203], s[64:65]
	global_store_dwordx2 v82, v[206:207], s[64:65] offset:512
	global_store_dwordx2 v82, v[210:211], s[64:65] offset:1024
	global_store_dwordx2 v82, v[214:215], s[64:65] offset:1536
	s_add_u32 s64, s64, 0x800
	s_addc_u32 s65, s65, 0
	v_pk_mul_f32 v[218:219], v[84:85], v[218:219] op_sel_hi:[0,1]
	v_pk_mul_f32 v[220:221], v[84:85], v[220:221] op_sel_hi:[0,1]
	v_pk_mul_f32 v[222:223], v[84:85], v[222:223] op_sel_hi:[0,1]
	v_pk_mul_f32 v[224:225], v[84:85], v[224:225] op_sel_hi:[0,1]
	v_pk_mul_f32 v[226:227], v[84:85], v[226:227] op_sel_hi:[0,1]
	v_pk_mul_f32 v[228:229], v[84:85], v[228:229] op_sel_hi:[0,1]
	v_pk_mul_f32 v[230:231], v[84:85], v[230:231] op_sel_hi:[0,1]
	v_pk_mul_f32 v[232:233], v[84:85], v[232:233] op_sel_hi:[0,1]
	v_pk_fma_f32 v[218:219], v[218:219], v[2:3], v[34:35]
	v_pk_fma_f32 v[220:221], v[220:221], v[4:5], v[36:37]
	v_pk_fma_f32 v[222:223], v[222:223], v[6:7], v[38:39]
	v_pk_fma_f32 v[224:225], v[224:225], v[8:9], v[40:41]
	v_pk_fma_f32 v[226:227], v[226:227], v[10:11], v[42:43]
	v_pk_fma_f32 v[228:229], v[228:229], v[12:13], v[44:45]
	v_pk_fma_f32 v[230:231], v[230:231], v[14:15], v[46:47]
	v_pk_fma_f32 v[232:233], v[232:233], v[16:17], v[48:49]
	v_cvt_pk_bf16_f32 v218, v218, v219
	v_cvt_pk_bf16_f32 v219, v220, v221
	v_cvt_pk_bf16_f32 v222, v222, v223
	v_cvt_pk_bf16_f32 v223, v224, v225
	v_cvt_pk_bf16_f32 v226, v226, v227
	v_cvt_pk_bf16_f32 v227, v228, v229
	v_cvt_pk_bf16_f32 v230, v230, v231
	v_cvt_pk_bf16_f32 v231, v232, v233
	global_store_dwordx2 v82, v[218:219], s[64:65]
	global_store_dwordx2 v82, v[222:223], s[64:65] offset:512
	global_store_dwordx2 v82, v[226:227], s[64:65] offset:1024
	global_store_dwordx2 v82, v[230:231], s[64:65] offset:1536
	s_add_u32 s64, s64, 0x800
	s_addc_u32 s65, s65, 0
	s_mov_b64 s[52:53], 0
